# v58 + MLA attention: context workgroups prefetch the next unit's query rows (next head) into free VGPRs during the current unit
# baseline (speedup 1.0000x reference)
.LBB0_652:
	v_add_u32_e32 v156, s40, v139
	s_mul_i32 s40, s55, 0x60
	v_mov_b64_e32 v[2:3], s[14:15]
	s_ashr_i32 s41, s40, 31
	v_mad_i64_i32 v[2:3], s[12:13], v156, s19, v[2:3]
	v_lshl_add_u64 v[2:3], s[40:41], 1, v[2:3]
	v_lshlrev_b32_e32 v0, 1, v138
	v_lshl_add_u64 v[2:3], v[2:3], 0, v[0:1]
	v_mov_b32_e32 v220, v2
	v_mov_b32_e32 v221, v3
	s_cmp_lg_u64 s[70:71], 0
	s_cbranch_scc1 .Latq_ld0
	s_cmp_eq_u32 s47, 0
	s_cbranch_scc1 .Latq_ld0
	s_cmp_eq_u64 s[62:63], 0
	s_cbranch_scc1 .Latq_ld0
	v_mov_b32_e32 v18, v234
	v_mov_b32_e32 v19, v235
	v_mov_b32_e32 v20, v236
	v_mov_b32_e32 v21, v237
	v_mov_b32_e32 v22, v238
	v_mov_b32_e32 v23, v239
	v_mov_b32_e32 v24, v240
	v_mov_b32_e32 v25, v241
	v_mov_b32_e32 v44, v242
	v_mov_b32_e32 v45, v243
	v_mov_b32_e32 v46, v244
	v_mov_b32_e32 v47, v245
	global_load_dwordx4 v[234:237], v[144:145], off
	global_load_dwordx4 v[238:241], v[144:145], off
	global_load_dwordx4 v[242:245], v[144:145], off
	s_branch .Latq_done0
.Latq_ld0:
	global_load_dwordx4 v[18:21], v[2:3], off
	global_load_dwordx4 v[22:25], v[2:3], off offset:64
	global_load_dwordx4 v[44:47], v[2:3], off offset:128
.Latq_done0:
	s_nop 0
	global_load_dwordx4 v[2:5], v[144:145], off offset:16
	global_load_dwordx4 v[10:13], v[144:145], off
	global_load_dwordx4 v[48:51], v[144:145], off offset:272
	global_load_dwordx4 v[52:55], v[144:145], off offset:256
	global_load_dwordx4 v[6:9], v[144:145], off offset:144
	global_load_dwordx4 v[14:17], v[144:145], off offset:128
	s_waitcnt vmcnt(28)
	v_and_b32_e32 v27, 64, v232
	v_xor_b32_e32 v26, 16, v232
	s_waitcnt vmcnt(24)
	v_add_u32_e32 v43, 64, v27
	v_cmp_lt_i32_e32 vcc, v26, v43
	v_ashrrev_i32_e32 v157, 31, v156
	s_waitcnt vmcnt(8)
	v_and_b32_e32 v41, 0xffff0000, v18
	v_cndmask_b32_e32 v26, v232, v26, vcc
	v_lshlrev_b32_e32 v155, 2, v26
	v_lshlrev_b32_e32 v42, 16, v18
	v_mul_f32_e32 v26, v41, v41
	v_lshlrev_b32_e32 v40, 16, v19
	v_fmac_f32_e32 v26, v42, v42
	v_and_b32_e32 v39, 0xffff0000, v19
	v_fmac_f32_e32 v26, v40, v40
	v_lshlrev_b32_e32 v38, 16, v20
	v_fmac_f32_e32 v26, v39, v39
	v_and_b32_e32 v37, 0xffff0000, v20
	v_fmac_f32_e32 v26, v38, v38
	v_lshlrev_b32_e32 v36, 16, v21
	v_fmac_f32_e32 v26, v37, v37
	v_and_b32_e32 v35, 0xffff0000, v21
	v_fmac_f32_e32 v26, v36, v36
	s_waitcnt vmcnt(7)
	v_lshlrev_b32_e32 v34, 16, v22
	v_fmac_f32_e32 v26, v35, v35
	v_and_b32_e32 v33, 0xffff0000, v22
	v_fmac_f32_e32 v26, v34, v34
	v_lshlrev_b32_e32 v32, 16, v23
	v_fmac_f32_e32 v26, v33, v33
	v_and_b32_e32 v31, 0xffff0000, v23
	v_fmac_f32_e32 v26, v32, v32
	v_lshlrev_b32_e32 v30, 16, v24
	v_fmac_f32_e32 v26, v31, v31
	v_and_b32_e32 v29, 0xffff0000, v24
	v_fmac_f32_e32 v26, v30, v30
	v_lshlrev_b32_e32 v28, 16, v25
	v_fmac_f32_e32 v26, v29, v29
	v_and_b32_e32 v27, 0xffff0000, v25
	s_waitcnt vmcnt(6)
	v_and_b32_e32 v25, 0xffff0000, v44
	v_lshlrev_b32_e32 v24, 16, v44
	v_fmac_f32_e32 v26, v28, v28
	v_pk_mul_f32 v[58:59], v[24:25], v[24:25]
	v_fmac_f32_e32 v26, v27, v27
	v_and_b32_e32 v23, 0xffff0000, v45
	v_lshlrev_b32_e32 v22, 16, v45
	v_add_f32_e32 v26, v58, v26
	v_pk_mul_f32 v[56:57], v[22:23], v[22:23]
	v_add_f32_e32 v26, v59, v26
	v_and_b32_e32 v21, 0xffff0000, v46
	v_lshlrev_b32_e32 v20, 16, v46
	v_add_f32_e32 v26, v56, v26
	v_and_b32_e32 v19, 0xffff0000, v47
	v_lshlrev_b32_e32 v18, 16, v47
	v_pk_mul_f32 v[46:47], v[20:21], v[20:21]
	v_add_f32_e32 v26, v57, v26
	v_add_f32_e32 v26, v46, v26
	v_pk_mul_f32 v[44:45], v[18:19], v[18:19]
	v_add_f32_e32 v26, v47, v26
	v_add_f32_e32 v26, v44, v26
	v_add_f32_e32 v26, v45, v26
	ds_bpermute_b32 v44, v155, v26
	v_xor_b32_e32 v45, 32, v232
	v_cmp_lt_i32_e32 vcc, v45, v43
	s_waitcnt lgkmcnt(0)
	v_add_f32_e32 v26, v26, v44
	v_cndmask_b32_e32 v43, v232, v45, vcc
	v_lshlrev_b32_e32 v176, 2, v43
	ds_bpermute_b32 v43, v176, v26
	v_cndmask_b32_e64 v44, 0, 1, s[70:71]
	v_cmp_ne_u32_e64 s[12:13], 1, v44
	s_andn2_b64 vcc, exec, s[70:71]
	s_waitcnt lgkmcnt(0)
	v_add_f32_e32 v26, v26, v43
	v_fmamk_f32 v26, v26, 0x3c2aaaab, v227
	v_rsq_f32_e32 v26, v26
	s_nop 0
	v_pk_mul_f32 v[24:25], v[26:27], v[24:25] op_sel_hi:[0,1]
	v_pk_mul_f32 v[22:23], v[26:27], v[22:23] op_sel_hi:[0,1]
	v_pk_mul_f32 v[20:21], v[26:27], v[20:21] op_sel_hi:[0,1]
	v_pk_mul_f32 v[18:19], v[26:27], v[18:19] op_sel_hi:[0,1]
	s_waitcnt vmcnt(2)
	v_pk_mul_f32 v[24:25], v[52:53], v[24:25]
	v_pk_mul_f32 v[22:23], v[54:55], v[22:23]
	v_pk_mul_f32 v[20:21], v[48:49], v[20:21]
	v_pk_mul_f32 v[18:19], v[50:51], v[18:19]
	s_cbranch_vccnz .LBB0_654
	v_and_b32_e32 v43, 63, v156
	v_bfe_u32 v44, v156, 6, 4
	v_cndmask_b32_e64 v43, v43, v44, s[8:9]
	v_lshlrev_b32_e32 v43, 6, v43
	global_load_dwordx4 v[44:47], v43, s[26:27] offset:48
	global_load_dwordx4 v[48:51], v43, s[26:27] offset:32
	global_load_dwordx4 v[52:55], v43, s[26:27] offset:16
	global_load_dwordx4 v[56:59], v43, s[26:27]
	ds_bpermute_b32 v60, v155, v24
	ds_bpermute_b32 v61, v155, v25
	s_waitcnt vmcnt(0)
	v_mov_b32_e32 v63, v58
	v_mov_b32_e32 v58, v57
	v_mov_b32_e32 v62, v56
	s_waitcnt lgkmcnt(0)
	v_pk_mul_f32 v[56:57], v[58:59], v[60:61]
	v_mov_b32_e32 v59, v54
	v_cndmask_b32_e64 v57, v57, -v57, s[10:11]
	v_cndmask_b32_e64 v56, v56, -v56, s[10:11]
	v_pk_fma_f32 v[24:25], v[24:25], v[62:63], v[56:57]
	ds_bpermute_b32 v56, v155, v22
	ds_bpermute_b32 v57, v155, v23
	v_mov_b32_e32 v54, v53
	v_mov_b32_e32 v58, v52
	s_waitcnt lgkmcnt(0)
	v_pk_mul_f32 v[52:53], v[54:55], v[56:57]
	s_nop 0
	v_cndmask_b32_e64 v53, v53, -v53, s[10:11]
	v_cndmask_b32_e64 v52, v52, -v52, s[10:11]
	v_pk_fma_f32 v[22:23], v[22:23], v[58:59], v[52:53]
	ds_bpermute_b32 v52, v155, v20
	ds_bpermute_b32 v53, v155, v21
	v_mov_b32_e32 v55, v50
	v_mov_b32_e32 v50, v49
	v_mov_b32_e32 v54, v48
	s_waitcnt lgkmcnt(0)
	v_pk_mul_f32 v[48:49], v[50:51], v[52:53]
	s_nop 0
	v_cndmask_b32_e64 v49, v49, -v49, s[10:11]
	v_cndmask_b32_e64 v48, v48, -v48, s[10:11]
	v_pk_fma_f32 v[20:21], v[20:21], v[54:55], v[48:49]
	ds_bpermute_b32 v48, v155, v18
	ds_bpermute_b32 v49, v155, v19
	v_mov_b32_e32 v51, v46
	v_mov_b32_e32 v46, v45
	v_mov_b32_e32 v50, v44
	s_waitcnt lgkmcnt(0)
	v_pk_mul_f32 v[44:45], v[46:47], v[48:49]
	s_nop 0
	v_cndmask_b32_e64 v45, v45, -v45, s[10:11]
	v_cndmask_b32_e64 v44, v44, -v44, s[10:11]
	v_pk_fma_f32 v[18:19], v[18:19], v[50:51], v[44:45]
.LBB0_654:
	v_mul_f32_e32 v38, v26, v38
	v_mul_f32_e32 v38, v2, v38
	v_mul_f32_e32 v2, v26, v37
	v_mul_f32_e32 v37, v3, v2
	v_mul_f32_e32 v2, v26, v36
	v_mul_f32_e32 v36, v4, v2
	v_mul_f32_e32 v2, v26, v35
	v_mul_f32_e32 v5, v5, v2
	v_mul_f32_e32 v2, v26, v34
	s_waitcnt vmcnt(0)
	v_mul_f32_e32 v14, v14, v2
	v_mul_f32_e32 v2, v26, v33
	v_mul_f32_e32 v15, v15, v2
	v_mul_f32_e32 v2, v26, v32
	v_mul_f32_e32 v16, v16, v2
	v_mul_f32_e32 v2, v26, v31
	v_mul_f32_e32 v17, v17, v2
	v_mul_f32_e32 v2, v26, v30
	v_mul_f32_e32 v30, v6, v2
	v_mul_f32_e32 v2, v26, v29
	v_mul_f32_e32 v29, v7, v2
	v_mul_f32_e32 v2, v26, v28
	v_mul_f32_e32 v42, v26, v42
	v_mul_f32_e32 v41, v26, v41
	v_mul_f32_e32 v40, v26, v40
	v_mul_f32_e32 v39, v26, v39
	v_mul_f32_e32 v28, v8, v2
	v_mul_f32_e32 v2, v26, v27
	v_mul_f32_e32 v10, v10, v42
	v_mul_f32_e32 v11, v11, v41
	v_mul_f32_e32 v12, v12, v40
	v_mul_f32_e32 v13, v13, v39
	v_mul_f32_e32 v9, v9, v2
	v_cvt_pk_bf16_f32 v2, v10, v11
	v_cvt_pk_bf16_f32 v3, v12, v13
	v_cvt_pk_bf16_f32 v4, v38, v37
	v_cvt_pk_bf16_f32 v5, v36, v5
	v_cvt_pk_bf16_f32 v6, v14, v15
	v_add_u32_e32 v158, 16, v156
	v_mov_b64_e32 v[14:15], s[14:15]
	v_mad_i64_i32 v[14:15], s[56:57], v158, s19, v[14:15]
	v_lshl_add_u64 v[14:15], s[40:41], 1, v[14:15]
	v_lshl_add_u64 v[14:15], v[14:15], 0, v[0:1]
	v_cvt_pk_bf16_f32 v7, v16, v17
	v_cvt_pk_bf16_f32 v8, v30, v29
	v_cvt_pk_bf16_f32 v9, v28, v9
	v_cvt_pk_bf16_f32 v10, v24, v25
	v_cvt_pk_bf16_f32 v11, v22, v23
	v_cvt_pk_bf16_f32 v12, v20, v21
	v_cvt_pk_bf16_f32 v13, v18, v19
	v_mov_b32_e32 v250, v14
	v_mov_b32_e32 v251, v15
	s_cmp_lg_u64 s[70:71], 0
	s_cbranch_scc1 .Latq_ld1
	s_cmp_eq_u32 s47, 0
	s_cbranch_scc1 .Latq_ld1
	s_cmp_eq_u64 s[62:63], 0
	s_cbranch_scc1 .Latq_ld1
	v_mov_b32_e32 v30, v246
	v_mov_b32_e32 v31, v247
	v_mov_b32_e32 v32, v248
	v_mov_b32_e32 v33, v249
	v_mov_b32_e32 v34, v228
	v_mov_b32_e32 v35, v229
	v_mov_b32_e32 v36, v230
	v_mov_b32_e32 v37, v231
	v_mov_b32_e32 v54, v222
	v_mov_b32_e32 v55, v223
	v_mov_b32_e32 v56, v224
	v_mov_b32_e32 v57, v225
	global_load_dwordx4 v[246:249], v[144:145], off
	global_load_dwordx4 v[228:231], v[144:145], off
	global_load_dwordx4 v[222:225], v[144:145], off
	s_branch .Latq_done1
.Latq_ld1:
	global_load_dwordx4 v[30:33], v[14:15], off
	global_load_dwordx4 v[34:37], v[14:15], off offset:64
	global_load_dwordx4 v[54:57], v[14:15], off offset:128
.Latq_done1:
	global_load_dwordx4 v[58:61], v[144:145], off offset:272
	global_load_dwordx4 v[62:65], v[144:145], off offset:256
	global_load_dwordx4 v[22:25], v[144:145], off offset:16
	global_load_dwordx4 v[26:29], v[144:145], off
	s_nop 0
	global_load_dwordx4 v[14:17], v[144:145], off offset:144
	global_load_dwordx4 v[18:21], v[144:145], off offset:128
	s_and_b64 vcc, exec, s[12:13]
	v_ashrrev_i32_e32 v159, 31, v158
	s_waitcnt vmcnt(8)
	v_and_b32_e32 v52, 0xffff0000, v30
	v_lshlrev_b32_e32 v53, 16, v30
	v_mul_f32_e32 v0, v52, v52
	v_lshlrev_b32_e32 v51, 16, v31
	v_fmac_f32_e32 v0, v53, v53
	v_and_b32_e32 v50, 0xffff0000, v31
	v_fmac_f32_e32 v0, v51, v51
	v_lshlrev_b32_e32 v49, 16, v32
	v_fmac_f32_e32 v0, v50, v50
	v_and_b32_e32 v48, 0xffff0000, v32
	v_fmac_f32_e32 v0, v49, v49
	v_lshlrev_b32_e32 v47, 16, v33
	v_fmac_f32_e32 v0, v48, v48
	v_and_b32_e32 v46, 0xffff0000, v33
	v_fmac_f32_e32 v0, v47, v47
	s_waitcnt vmcnt(7)
	v_lshlrev_b32_e32 v45, 16, v34
	v_fmac_f32_e32 v0, v46, v46
	v_and_b32_e32 v44, 0xffff0000, v34
	v_fmac_f32_e32 v0, v45, v45
	v_lshlrev_b32_e32 v43, 16, v35
	v_fmac_f32_e32 v0, v44, v44
	v_and_b32_e32 v42, 0xffff0000, v35
	v_fmac_f32_e32 v0, v43, v43
	v_lshlrev_b32_e32 v41, 16, v36
	v_fmac_f32_e32 v0, v42, v42
	v_and_b32_e32 v40, 0xffff0000, v36
	v_fmac_f32_e32 v0, v41, v41
	v_lshlrev_b32_e32 v39, 16, v37
	v_fmac_f32_e32 v0, v40, v40
	v_and_b32_e32 v38, 0xffff0000, v37
	s_waitcnt vmcnt(6)
	v_and_b32_e32 v37, 0xffff0000, v54
	v_fmac_f32_e32 v0, v39, v39
	v_lshlrev_b32_e32 v36, 16, v54
	v_and_b32_e32 v35, 0xffff0000, v55
	v_lshlrev_b32_e32 v34, 16, v55
	v_fmac_f32_e32 v0, v38, v38
	v_pk_mul_f32 v[54:55], v[36:37], v[36:37]
	v_pk_mul_f32 v[68:69], v[34:35], v[34:35]
	v_add_f32_e32 v0, v54, v0
	v_add_f32_e32 v0, v55, v0
	v_and_b32_e32 v33, 0xffff0000, v56
	v_lshlrev_b32_e32 v32, 16, v56
	v_add_f32_e32 v0, v68, v0
	v_pk_mul_f32 v[66:67], v[32:33], v[32:33]
	v_add_f32_e32 v0, v69, v0
	v_and_b32_e32 v31, 0xffff0000, v57
	v_lshlrev_b32_e32 v30, 16, v57
	v_add_f32_e32 v0, v66, v0
	v_pk_mul_f32 v[56:57], v[30:31], v[30:31]
	v_add_f32_e32 v0, v67, v0
	v_add_f32_e32 v0, v56, v0
	v_add_f32_e32 v0, v57, v0
	ds_bpermute_b32 v54, v155, v0
	s_waitcnt lgkmcnt(0)
	v_add_f32_e32 v0, v0, v54
	ds_bpermute_b32 v54, v176, v0
	s_waitcnt lgkmcnt(0)
	v_add_f32_e32 v0, v0, v54
	v_fmamk_f32 v0, v0, 0x3c2aaaab, v227
	v_rsq_f32_e32 v0, v0
	s_nop 0
	v_pk_mul_f32 v[36:37], v[0:1], v[36:37] op_sel_hi:[0,1]
	v_pk_mul_f32 v[34:35], v[0:1], v[34:35] op_sel_hi:[0,1]
	v_pk_mul_f32 v[32:33], v[0:1], v[32:33] op_sel_hi:[0,1]
	v_pk_mul_f32 v[30:31], v[0:1], v[30:31] op_sel_hi:[0,1]
	s_waitcnt vmcnt(4)
	v_pk_mul_f32 v[36:37], v[62:63], v[36:37]
	v_pk_mul_f32 v[34:35], v[64:65], v[34:35]
	v_pk_mul_f32 v[32:33], v[58:59], v[32:33]
	v_pk_mul_f32 v[30:31], v[60:61], v[30:31]
	s_cbranch_vccnz .LBB0_656
	v_and_b32_e32 v54, 63, v158
	v_bfe_u32 v55, v158, 6, 4
	v_cndmask_b32_e64 v54, v54, v55, s[8:9]
	v_lshlrev_b32_e32 v66, 6, v54
	global_load_dwordx4 v[54:57], v66, s[26:27] offset:48
	global_load_dwordx4 v[58:61], v66, s[26:27] offset:32
	global_load_dwordx4 v[62:65], v66, s[26:27] offset:16
	s_nop 0
	global_load_dwordx4 v[66:69], v66, s[26:27]
	ds_bpermute_b32 v70, v155, v36
	ds_bpermute_b32 v71, v155, v37
	s_waitcnt vmcnt(0)
	v_mov_b32_e32 v73, v68
	v_mov_b32_e32 v68, v67
	v_mov_b32_e32 v72, v66
	s_waitcnt lgkmcnt(0)
	v_pk_mul_f32 v[66:67], v[68:69], v[70:71]
	v_mov_b32_e32 v69, v64
	v_cndmask_b32_e64 v67, v67, -v67, s[10:11]
	v_cndmask_b32_e64 v66, v66, -v66, s[10:11]
	v_pk_fma_f32 v[36:37], v[36:37], v[72:73], v[66:67]
	ds_bpermute_b32 v66, v155, v34
	ds_bpermute_b32 v67, v155, v35
	v_mov_b32_e32 v64, v63
	v_mov_b32_e32 v68, v62
	s_waitcnt lgkmcnt(0)
	v_pk_mul_f32 v[62:63], v[64:65], v[66:67]
	s_nop 0
	v_cndmask_b32_e64 v63, v63, -v63, s[10:11]
	v_cndmask_b32_e64 v62, v62, -v62, s[10:11]
	v_pk_fma_f32 v[34:35], v[34:35], v[68:69], v[62:63]
	ds_bpermute_b32 v62, v155, v32
	ds_bpermute_b32 v63, v155, v33
	v_mov_b32_e32 v65, v60
	v_mov_b32_e32 v60, v59
	v_mov_b32_e32 v64, v58
	s_waitcnt lgkmcnt(0)
	v_pk_mul_f32 v[58:59], v[60:61], v[62:63]
	s_nop 0
	v_cndmask_b32_e64 v59, v59, -v59, s[10:11]
	v_cndmask_b32_e64 v58, v58, -v58, s[10:11]
	v_pk_fma_f32 v[32:33], v[32:33], v[64:65], v[58:59]
	ds_bpermute_b32 v58, v155, v30
	ds_bpermute_b32 v59, v155, v31
	v_mov_b32_e32 v61, v56
	v_mov_b32_e32 v56, v55
	v_mov_b32_e32 v60, v54
	s_waitcnt lgkmcnt(0)
	v_pk_mul_f32 v[54:55], v[56:57], v[58:59]
	s_nop 0
	v_cndmask_b32_e64 v55, v55, -v55, s[10:11]
	v_cndmask_b32_e64 v54, v54, -v54, s[10:11]
	v_pk_fma_f32 v[30:31], v[30:31], v[60:61], v[54:55]
.LBB0_656:
	s_lshl_b32 s12, s55, 6
	s_lshl_b64 s[56:57], s[40:41], 1
	v_mul_f32_e32 v41, v0, v41
	s_add_u32 s40, s48, s56
	v_mul_f32_e32 v53, v0, v53
	v_mul_f32_e32 v52, v0, v52
	s_waitcnt vmcnt(1)
	v_mul_f32_e32 v41, v14, v41
	v_mul_f32_e32 v14, v0, v40
	s_addc_u32 s41, s49, s57
	s_ashr_i32 s13, s12, 31
	v_mul_f32_e32 v26, v26, v53
	v_mul_f32_e32 v27, v27, v52
	v_mul_f32_e32 v40, v15, v14
	v_mul_f32_e32 v14, v0, v39
	s_lshl_b64 s[12:13], s[12:13], 1
	v_mul_f32_e32 v45, v0, v45
	v_mul_f32_e32 v44, v0, v44
	v_mul_f32_e32 v43, v0, v43
	v_mul_f32_e32 v42, v0, v42
	v_mul_f32_e32 v39, v16, v14
	v_cvt_pk_bf16_f32 v14, v26, v27
	v_lshl_add_u64 v[26:27], s[52:53], 0, v[150:151]
	s_add_u32 s60, s40, 0x30000
	v_mul_f32_e32 v51, v0, v51
	v_mul_f32_e32 v50, v0, v50
	v_mul_f32_e32 v49, v0, v49
	v_mul_f32_e32 v48, v0, v48
	v_mul_f32_e32 v47, v0, v47
	v_mul_f32_e32 v46, v0, v46
	s_waitcnt vmcnt(0)
	v_mul_f32_e32 v18, v18, v45
	v_mul_f32_e32 v19, v19, v44
	v_mul_f32_e32 v20, v20, v43
	v_mul_f32_e32 v21, v21, v42
	v_mul_f32_e32 v0, v0, v38
	v_lshl_add_u64 v[26:27], v[26:27], 0, s[12:13]
	v_lshlrev_b64 v[62:63], 1, v[146:147]
	v_lshlrev_b64 v[66:67], 1, v[148:149]
	s_addc_u32 s61, s41, 0
	v_mul_f32_e32 v28, v28, v51
	v_mul_f32_e32 v29, v29, v50
	v_mul_f32_e32 v22, v22, v49
	v_mul_f32_e32 v23, v23, v48
	v_mul_f32_e32 v24, v24, v47
	v_mul_f32_e32 v25, v25, v46
	v_mul_f32_e32 v0, v17, v0
	v_cvt_pk_bf16_f32 v15, v28, v29
	v_cvt_pk_bf16_f32 v16, v22, v23
	v_cvt_pk_bf16_f32 v17, v24, v25
	v_cvt_pk_bf16_f32 v18, v18, v19
	v_cvt_pk_bf16_f32 v19, v20, v21
	v_cvt_pk_bf16_f32 v20, v41, v40
	v_cvt_pk_bf16_f32 v21, v39, v0
	v_lshl_add_u64 v[70:71], v[26:27], 0, v[152:153]
	v_lshl_add_u64 v[38:39], s[60:61], 0, v[62:63]
	v_lshl_add_u64 v[40:41], s[60:61], 0, v[66:67]
	s_mov_b32 s4, 0x20000
	s_add_u32 s60, s40, 0x60000
	v_add_co_u32_e32 v46, vcc, s4, v70
	s_addc_u32 s61, s41, 0
	v_lshl_add_u64 v[26:27], s[40:41], 0, v[62:63]
	v_lshl_add_u64 v[28:29], s[40:41], 0, v[66:67]
	v_addc_co_u32_e32 v47, vcc, 0, v71, vcc
	s_mov_b32 s4, 0x40000
	s_add_u32 s40, s40, 0x90000
	v_lshlrev_b64 v[64:65], 1, v[140:141]
	v_lshlrev_b64 v[68:69], 1, v[142:143]
	v_add_co_u32_e32 v58, vcc, s4, v70
	s_addc_u32 s41, s41, 0
	v_cvt_pk_bf16_f32 v22, v36, v37
	v_cvt_pk_bf16_f32 v23, v34, v35
	v_cvt_pk_bf16_f32 v24, v32, v33
	v_cvt_pk_bf16_f32 v25, v30, v31
	v_lshl_add_u64 v[26:27], v[26:27], 0, v[64:65]
	v_lshl_add_u64 v[30:31], v[28:29], 0, v[68:69]
	v_lshl_add_u64 v[50:51], s[60:61], 0, v[62:63]
	v_addc_co_u32_e32 v59, vcc, 0, v71, vcc
	v_lshl_add_u64 v[62:63], s[40:41], 0, v[62:63]
	s_mov_b32 s4, 0x60000
	s_cmp_lg_u64 s[70:71], 0
	s_cbranch_scc1 .Latq_noissue
	s_cmp_lt_u32 s47, 3
	s_cbranch_scc0 .Latq_noissue
	s_cmp_eq_u64 s[62:63], 0
	s_cbranch_scc1 .Latq_noissue
	global_load_dwordx4 v[234:237], v[220:221], off offset:192
	global_load_dwordx4 v[238:241], v[220:221], off offset:256
	global_load_dwordx4 v[242:245], v[220:221], off offset:320
	global_load_dwordx4 v[246:249], v[250:251], off offset:192
	global_load_dwordx4 v[228:231], v[250:251], off offset:256
	global_load_dwordx4 v[222:225], v[250:251], off offset:320
.Latq_noissue:
	global_load_dwordx4 v[26:29], v[26:27], off
	s_nop 0
	global_load_dwordx4 v[30:33], v[30:31], off
	s_nop 0
	global_load_dwordx4 v[34:37], v[70:71], off
	v_lshl_add_u64 v[38:39], v[38:39], 0, v[64:65]
	v_lshl_add_u64 v[50:51], v[50:51], 0, v[64:65]
	v_lshl_add_u64 v[52:53], s[60:61], 0, v[66:67]
	v_lshl_add_u64 v[62:63], v[62:63], 0, v[64:65]
	v_lshl_add_u64 v[64:65], s[40:41], 0, v[66:67]
	v_add_co_u32_e32 v70, vcc, s4, v70
	v_lshl_add_u64 v[42:43], v[40:41], 0, v[68:69]
	v_lshl_add_u64 v[54:55], v[52:53], 0, v[68:69]
	v_lshl_add_u64 v[66:67], v[64:65], 0, v[68:69]
	v_addc_co_u32_e32 v71, vcc, 0, v71, vcc
	global_load_dwordx4 v[38:41], v[38:39], off
	s_nop 0
	global_load_dwordx4 v[42:45], v[42:43], off
	s_add_i32 s55, s54, -1
	global_load_dwordx4 v[46:49], v[46:47], off
	s_nop 0
	global_load_dwordx4 v[50:53], v[50:51], off
	s_nop 0
	global_load_dwordx4 v[54:57], v[54:55], off
	s_cmp_eq_u32 s55, 3
	global_load_dwordx4 v[58:61], v[58:59], off
	s_nop 0
	global_load_dwordx4 v[62:65], v[62:63], off
	s_nop 0
	global_load_dwordx4 v[66:69], v[66:67], off
	s_cselect_b64 s[40:41], -1, 0
	global_load_dwordx4 v[70:73], v[70:71], off
	s_and_b64 s[60:61], s[40:41], exec
	s_cselect_b32 s45, s53, s45
	s_cselect_b32 s44, s52, s44
	v_lshl_add_u64 v[74:75], s[44:45], 0, v[150:151]
	s_cselect_b32 s42, s48, s42
	v_lshl_add_u64 v[74:75], v[74:75], 0, s[12:13]
	v_mov_b32_e32 v76, v1
	v_mov_b32_e32 v77, v1
	s_cselect_b32 s4, s49, s43
	s_add_u32 s42, s42, s56
	v_lshl_add_u64 v[162:163], v[74:75], 0, v[152:153]
	v_mov_b32_e32 v179, v178
	v_mov_b32_e32 v0, v1
	v_mov_b32_e32 v74, v1
	v_mov_b32_e32 v75, v1
	v_mov_b64_e32 v[80:81], v[76:77]
	v_mov_b64_e32 v[84:85], v[76:77]
	v_mov_b64_e32 v[88:89], v[76:77]
	v_mov_b64_e32 v[92:93], v[76:77]
	v_mov_b64_e32 v[96:97], v[76:77]
	v_mov_b64_e32 v[100:101], v[76:77]
	v_mov_b64_e32 v[104:105], v[76:77]
	s_addc_u32 s43, s4, s57
	s_mov_b32 s44, 7
	v_mov_b64_e32 v[78:79], v[74:75]
	v_mov_b64_e32 v[82:83], v[74:75]
	v_mov_b64_e32 v[86:87], v[74:75]
	v_mov_b64_e32 v[90:91], v[74:75]
	v_mov_b64_e32 v[94:95], v[74:75]
	v_mov_b64_e32 v[98:99], v[74:75]
	v_mov_b64_e32 v[102:103], v[74:75]
	v_mov_b64_e32 v[160:161], v[0:1]
	v_mov_b64_e32 v[166:167], v[178:179]
	s_branch .LBB0_658
